# steady attention loop: slot rotation, address increments and exit test moved in front of the closing barrier (loop-edge rotation)
# baseline (speedup 1.0000x reference)
; #define WAIT_BAR(N) asm volatile("s_waitcnt vmcnt(" #N ") lgkmcnt(0)\n\ts_barrier":::"memory")
;   #define RESC() do{ if(resc){ asm volatile("s_waitcnt lgkmcnt(0)":::"memory"); \
;       _Pragma("unroll") for(int d_=0;d_<2;++d_) _Pragma("unroll") for(int r=0;r<16;++r)o[d_][r]*=wsf[crow(r,hi)]; } }while(0)
;   #define ROT() do{sl_prev=sl_cur;sl_cur=sl_next;sl_next=(sl_next==(NSLOT-1)*SLOTB)?0:sl_next+SLOTB;}while(0)
; template<int THRL> __device__ __forceinline__ void attn_unit(long rowbase,int qb,int t0,bool WIN,bool NOMAX,const bf16*Qc,const bf16*__restrict__ Kc,const bf16*__restrict__ Vc,bf16*Oc,float s2,float sink2,char*shm,
;     bf16x8 (&qr)[4],bool pref,const bf16*qkvb,int vn,int in_){
;     ...
;   int t=1;
;     ...
;   for(;t+5<NT;t+=2){
;     STEP(pB0,pB1,pA0,pA1,t,true,true,true);     WAIT_BAR(2); RESC(); ROT();
.LBB0_337:
	s_or_b64 exec, exec, s[64:65]
	s_waitcnt lgkmcnt(14)
	v_mfma_f32_32x32x16_bf16 v[18:33], v[142:145], v[84:87], v[18:33]
	v_exp_f32_e32 v66, v66
	v_exp_f32_e32 v67, v67
	s_waitcnt lgkmcnt(12)
	v_mfma_f32_32x32x16_bf16 v[34:49], v[142:145], v[88:91], v[34:49]
	v_exp_f32_e32 v68, v68
	v_exp_f32_e32 v69, v69
	v_add_u32_e32 v82, s66, v231
	ds_read_b128 v[162:165], v82
	ds_read_b128 v[158:161], v82 offset:512
	s_waitcnt lgkmcnt(12)
	v_mfma_f32_32x32x16_bf16 v[18:33], v[138:141], v[92:95], v[18:33]
	v_exp_f32_e32 v70, v70
	v_exp_f32_e32 v71, v71
	ds_read_b128 v[154:157], v82 offset:2048
	ds_read_b128 v[146:149], v82 offset:2560
	s_waitcnt lgkmcnt(12)
	v_mfma_f32_32x32x16_bf16 v[34:49], v[138:141], v[114:117], v[34:49]
	v_exp_f32_e32 v72, v72
	v_exp_f32_e32 v73, v73
	ds_read_b128 v[94:97], v82 offset:4096
	ds_read_b128 v[90:93], v82 offset:4608
	s_waitcnt lgkmcnt(12)
	v_mfma_f32_32x32x16_bf16 v[18:33], v[134:137], v[118:121], v[18:33]
	v_exp_f32_e32 v74, v74
	v_exp_f32_e32 v75, v75
	ds_read_b128 v[86:89], v82 offset:6144
	ds_read_b128 v[82:85], v82 offset:6656
	s_waitcnt lgkmcnt(12)
	v_mfma_f32_32x32x16_bf16 v[34:49], v[134:137], v[98:101], v[34:49]
	v_exp_f32_e32 v76, v76
	v_exp_f32_e32 v77, v77
	s_waitcnt lgkmcnt(10)
	v_mfma_f32_32x32x16_bf16 v[18:33], v[130:133], v[102:105], v[18:33]
	v_exp_f32_e32 v78, v78
	v_exp_f32_e32 v79, v79
	s_waitcnt lgkmcnt(8)
	v_mfma_f32_32x32x16_bf16 v[34:49], v[130:133], v[106:109], v[34:49]
	v_exp_f32_e32 v80, v80
	v_exp_f32_e32 v81, v81
	ds_read_b64_tr_b16 v[98:99], v255 offset:24576
	ds_read_b64_tr_b16 v[100:101], v255 offset:25088
	ds_read_b64_tr_b16 v[102:103], v255 offset:28672
	ds_read_b64_tr_b16 v[104:105], v255 offset:29184
	ds_read_b64_tr_b16 v[106:107], v255 offset:25600
	ds_read_b64_tr_b16 v[108:109], v255 offset:26112
	ds_read_b64_tr_b16 v[110:111], v255 offset:29696
	ds_read_b64_tr_b16 v[112:113], v255 offset:30208
	ds_read_b64_tr_b16 v[114:115], v255 offset:26624
	ds_read_b64_tr_b16 v[116:117], v255 offset:27136
	ds_read_b64_tr_b16 v[118:119], v255 offset:30720
	ds_read_b64_tr_b16 v[120:121], v255 offset:31232
	ds_read_b64_tr_b16 v[122:123], v255 offset:27648
	ds_read_b64_tr_b16 v[124:125], v255 offset:28160
	ds_read_b64_tr_b16 v[126:127], v255 offset:31744
	ds_read_b64_tr_b16 v[128:129], v255 offset:32256
	s_sub_i32 s64, s49, 64
	v_exp_f32_e32 v50, v50
	v_exp_f32_e32 v51, v51
	v_exp_f32_e32 v52, v52
	v_exp_f32_e32 v53, v53
	v_exp_f32_e32 v54, v54
	v_exp_f32_e32 v55, v55
	v_exp_f32_e32 v56, v56
	v_exp_f32_e32 v57, v57
	s_waitcnt lgkmcnt(14)
	v_mfma_f32_32x32x16_bf16 v[236:251], v[142:145], v[98:101], v[236:251]
	v_cvt_f32_u32_e32 v98, s64
	v_mov_b32_e32 v185, v184
	v_fma_f32 v98, v184, v98, v186
	v_sub_f32_e32 v98, v98, v225
	v_exp_f32_e32 v58, v58
	s_waitcnt lgkmcnt(12)
	v_mfma_f32_32x32x16_bf16 v[200:215], v[142:145], v[102:105], v[200:215]
	v_fma_f32 v105, v185, s31, v98
	v_fma_f32 v104, v184, s30, v98
	v_fma_f32 v103, v185, s35, v98
	v_fma_f32 v102, v184, s34, v98
	v_exp_f32_e32 v59, v59
	s_waitcnt lgkmcnt(10)
	v_mfma_f32_32x32x16_bf16 v[236:251], v[138:141], v[106:109], v[236:251]
	v_fma_f32 v109, v185, s27, v98
	v_fma_f32 v108, v184, s26, v98
	v_fma_f32 v107, v185, s29, v98
	v_fma_f32 v106, v184, s28, v98
	v_exp_f32_e32 v60, v60
	s_waitcnt lgkmcnt(8)
	v_mfma_f32_32x32x16_bf16 v[200:215], v[138:141], v[110:113], v[200:215]
	v_fma_f32 v113, v185, s23, v98
	v_fma_f32 v112, v184, s22, v98
	v_fma_f32 v111, v185, s25, v98
	v_fma_f32 v110, v184, s24, v98
	v_exp_f32_e32 v61, v61
	s_waitcnt lgkmcnt(6)
	v_mfma_f32_32x32x16_bf16 v[236:251], v[134:137], v[114:117], v[236:251]
	v_fma_f32 v114, 0, v184, v98
	v_add_f32_e32 v115, v184, v98
	v_fma_f32 v117, v191, s9, v98
	v_fma_f32 v116, v190, s8, v98
	v_exp_f32_e32 v62, v62
	s_waitcnt lgkmcnt(4)
	v_mfma_f32_32x32x16_bf16 v[200:215], v[134:137], v[118:121], v[200:215]
	v_fma_f32 v119, v191, s11, v98
	v_fma_f32 v118, v190, s10, v98
	v_fma_f32 v121, v191, s13, v98
	v_fma_f32 v120, v190, s12, v98
	v_exp_f32_e32 v63, v63
	s_waitcnt lgkmcnt(2)
	v_mfma_f32_32x32x16_bf16 v[236:251], v[130:133], v[122:125], v[236:251]
	v_fma_f32 v123, v191, s15, v98
	v_fma_f32 v122, v190, s14, v98
	v_fma_f32 v125, v191, s17, v98
	v_fma_f32 v124, v190, s16, v98
	v_exp_f32_e32 v64, v64
	s_waitcnt lgkmcnt(0)
	v_mfma_f32_32x32x16_bf16 v[200:215], v[130:133], v[126:129], v[200:215]
	v_fma_f32 v127, v191, s19, v98
	v_fma_f32 v126, v190, s18, v98
	v_fma_f32 v129, v191, s21, v98
	v_fma_f32 v128, v190, s20, v98
	v_exp_f32_e32 v65, v65
	v_fma_f32 v101, v185, s37, v98
	v_fma_f32 v100, v184, s36, v98
	v_fma_f32 v99, v189, s93, v98
	v_fma_f32 v98, v188, s92, v98
	v_lshl_add_u64 v[130:131], v[198:199], 0, s[94:95]
	s_add_i32 s100, s51, s50
	s_mov_b32 s101, m0
	s_mov_b32 m0, s100
	s_nop 0
	global_load_lds_dwordx4 v[130:131], off
	v_lshl_add_u64 v[130:131], v[196:197], 0, s[94:95]
	s_add_i32 s100, s66, s79
	s_mov_b32 m0, s100
	s_nop 0
	global_load_lds_dwordx4 v[130:131], off
	s_add_i32 m0, s100, 0xe780
	s_nop 0
	global_load_lds_dwordx4 v[130:131], off offset:128
	s_mov_b32 m0, s101
	s_add_i32 s100, s66, 0x2000
	s_cmpk_lg_i32 s66, 0x4000
	s_cselect_b32 s86, s100, 0
	s_nop 0
	s_waitcnt vmcnt(3) lgkmcnt(0)
	s_barrier
	s_and_saveexec_b64 s[64:65], s[44:45]
	s_cbranch_execz .LBB0_339
	s_waitcnt lgkmcnt(0)
	ds_read_b128 v[150:153], v227 offset:49248
	ds_read_b128 v[168:171], v227 offset:49216
	ds_read_b128 v[172:175], v227 offset:49184
	s_waitcnt lgkmcnt(2)
	v_pk_mul_f32 v[32:33], v[32:33], v[152:153]
	v_pk_mul_f32 v[30:31], v[30:31], v[150:151]
	v_pk_mul_f32 v[48:49], v[48:49], v[152:153]
	v_pk_mul_f32 v[46:47], v[46:47], v[150:151]
	v_pk_mul_f32 v[250:251], v[250:251], v[152:153]
	v_pk_mul_f32 v[248:249], v[248:249], v[150:151]
	v_pk_mul_f32 v[214:215], v[214:215], v[152:153]
	v_pk_mul_f32 v[212:213], v[212:213], v[150:151]
	ds_read_b128 v[150:153], v227 offset:49152
	s_waitcnt lgkmcnt(2)
	v_pk_mul_f32 v[28:29], v[28:29], v[170:171]
	v_pk_mul_f32 v[26:27], v[26:27], v[168:169]
	v_pk_mul_f32 v[44:45], v[44:45], v[170:171]
	v_pk_mul_f32 v[42:43], v[42:43], v[168:169]
	v_pk_mul_f32 v[246:247], v[246:247], v[170:171]
	v_pk_mul_f32 v[244:245], v[244:245], v[168:169]
	v_pk_mul_f32 v[210:211], v[210:211], v[170:171]
	v_pk_mul_f32 v[208:209], v[208:209], v[168:169]
	s_waitcnt lgkmcnt(1)
	v_pk_mul_f32 v[24:25], v[24:25], v[174:175]
	v_pk_mul_f32 v[22:23], v[22:23], v[172:173]
	v_pk_mul_f32 v[40:41], v[40:41], v[174:175]
	v_pk_mul_f32 v[38:39], v[38:39], v[172:173]
	v_pk_mul_f32 v[242:243], v[242:243], v[174:175]
	v_pk_mul_f32 v[240:241], v[240:241], v[172:173]
	v_pk_mul_f32 v[206:207], v[206:207], v[174:175]
	v_pk_mul_f32 v[204:205], v[204:205], v[172:173]
	s_waitcnt lgkmcnt(0)
	v_pk_mul_f32 v[20:21], v[20:21], v[152:153]
	v_pk_mul_f32 v[18:19], v[18:19], v[150:151]
	v_pk_mul_f32 v[36:37], v[36:37], v[152:153]
	v_pk_mul_f32 v[34:35], v[34:35], v[150:151]
	v_pk_mul_f32 v[238:239], v[238:239], v[152:153]
	v_pk_mul_f32 v[236:237], v[236:237], v[150:151]
	v_pk_mul_f32 v[202:203], v[202:203], v[152:153]
	v_pk_mul_f32 v[200:201], v[200:201], v[150:151]
.LBB0_339:
	s_or_b64 exec, exec, s[64:65]
	v_add_u32_e32 v167, s51, v232
	v_add_u32_e32 v255, 0xe800, v167
	ds_read_b64_tr_b16 v[150:151], v167 offset:24576
	ds_read_b64_tr_b16 v[152:153], v167 offset:25088
	s_waitcnt lgkmcnt(9)
	v_mfma_f32_32x32x16_bf16 v[114:129], v[162:165], v[2:5], v[114:129]
	v_add_f32_e32 v130, v66, v67
	v_add_f32_e32 v130, v68, v130
	v_add_f32_e32 v130, v69, v130
	v_add_f32_e32 v130, v70, v130
	v_add_f32_e32 v130, v71, v130
	v_cvt_pk_bf16_f32 v142, v66, v67
	v_cvt_pk_bf16_f32 v143, v68, v69
	ds_read_b64_tr_b16 v[66:67], v167 offset:28672
	ds_read_b64_tr_b16 v[68:69], v167 offset:29184
	s_waitcnt lgkmcnt(10)
	v_mfma_f32_32x32x16_bf16 v[98:113], v[158:161], v[2:5], v[98:113]
	v_add_f32_e32 v130, v72, v130
	v_add_f32_e32 v130, v73, v130
	v_add_f32_e32 v130, v74, v130
	v_add_f32_e32 v130, v75, v130
	v_cvt_pk_bf16_f32 v144, v70, v71
	v_cvt_pk_bf16_f32 v145, v72, v73
	ds_read_b64_tr_b16 v[70:71], v167 offset:25600
	ds_read_b64_tr_b16 v[72:73], v167 offset:26112
	s_waitcnt lgkmcnt(11)
	v_mfma_f32_32x32x16_bf16 v[114:129], v[154:157], v[6:9], v[114:129]
	v_add_f32_e32 v130, v76, v130
	v_add_f32_e32 v130, v77, v130
	v_add_f32_e32 v130, v78, v130
	v_add_f32_e32 v130, v79, v130
	v_cvt_pk_bf16_f32 v138, v74, v75
	v_cvt_pk_bf16_f32 v139, v76, v77
	ds_read_b64_tr_b16 v[74:75], v167 offset:29696
	ds_read_b64_tr_b16 v[76:77], v167 offset:30208
	s_waitcnt lgkmcnt(12)
	v_mfma_f32_32x32x16_bf16 v[98:113], v[146:149], v[6:9], v[98:113]
	v_add_f32_e32 v130, v80, v130
	v_add_f32_e32 v130, v81, v130
	v_add_f32_e32 v130, v50, v130
	v_add_f32_e32 v130, v51, v130
	v_cvt_pk_bf16_f32 v140, v78, v79
	v_cvt_pk_bf16_f32 v141, v80, v81
	ds_read_b64_tr_b16 v[78:79], v167 offset:26624
	ds_read_b64_tr_b16 v[80:81], v167 offset:27136
	s_waitcnt lgkmcnt(13)
	v_mfma_f32_32x32x16_bf16 v[114:129], v[94:97], v[10:13], v[114:129]
	v_add_f32_e32 v94, v52, v130
	v_add_f32_e32 v94, v53, v94
	v_add_f32_e32 v94, v54, v94
	v_add_f32_e32 v94, v55, v94
	v_cvt_pk_bf16_f32 v134, v50, v51
	v_cvt_pk_bf16_f32 v135, v52, v53
	ds_read_b64_tr_b16 v[50:51], v167 offset:30720
	ds_read_b64_tr_b16 v[52:53], v167 offset:31232
	s_waitcnt lgkmcnt(14)
	v_mfma_f32_32x32x16_bf16 v[98:113], v[90:93], v[10:13], v[98:113]
	v_add_f32_e32 v90, v56, v94
	v_add_f32_e32 v90, v57, v90
	v_add_f32_e32 v90, v58, v90
	v_add_f32_e32 v90, v59, v90
	v_cvt_pk_bf16_f32 v136, v54, v55
	v_cvt_pk_bf16_f32 v137, v56, v57
	ds_read_b64_tr_b16 v[54:55], v167 offset:27648
	ds_read_b64_tr_b16 v[56:57], v167 offset:28160
	s_waitcnt lgkmcnt(14)
	v_mfma_f32_32x32x16_bf16 v[114:129], v[86:89], v[14:17], v[114:129]
	v_add_f32_e32 v86, v60, v90
	v_add_f32_e32 v86, v61, v86
	v_add_f32_e32 v86, v62, v86
	v_add_f32_e32 v86, v63, v86
	v_cvt_pk_bf16_f32 v130, v58, v59
	v_cvt_pk_bf16_f32 v131, v60, v61
	ds_read_b64_tr_b16 v[58:59], v167 offset:31744
	ds_read_b64_tr_b16 v[60:61], v167 offset:32256
	v_mfma_f32_32x32x16_bf16 v[98:113], v[82:85], v[14:17], v[98:113]
	v_add_f32_e32 v82, v64, v86
	v_add_f32_e32 v82, v65, v82
	v_add_f32_e32 v82, 0, v82
	v_cvt_pk_bf16_f32 v132, v62, v63
	v_cvt_pk_bf16_f32 v133, v64, v65
	v_add_f32_e32 v82, v166, v82
	s_mov_b64 s[44:45], 0
	s_and_saveexec_b64 s[64:65], s[40:41]
	s_cbranch_execz .LBB0_342
	v_max_f32_e32 v62, v115, v115
	v_max_f32_e32 v63, v114, v114
	v_max_f32_e32 v62, v63, v62
	v_max3_f32 v63, v116, v117, v99
	v_max3_f32 v62, v62, v98, v100
	v_max3_f32 v62, v62, v101, v118
	v_max3_f32 v63, v63, v120, v121
	v_max3_f32 v62, v62, v119, v102
	v_max3_f32 v63, v63, v104, v105
	v_max3_f32 v62, v62, v103, v122
	v_max3_f32 v63, v63, v124, v125
	v_max3_f32 v62, v62, v123, v106
	v_max3_f32 v63, v63, v108, v109
	v_max3_f32 v62, v62, v107, v126
	v_max3_f32 v63, v63, v128, v129
	v_max3_f32 v62, v62, v127, v110
	v_max3_f32 v63, v63, v112, v113
	v_max3_f32 v62, v62, v111, v63
	v_mov_b32_e32 v63, v62
	s_nop 1
	v_permlane32_swap_b32_e32 v62, v63
	v_max_f32_e32 v63, v63, v63
	v_max_f32_e32 v62, v62, v62
	v_max_f32_e32 v62, v62, v63
	v_cmp_lt_f32_e32 vcc, s84, v62
	s_cbranch_vccnz .LBB0_349

; #define WAIT_BAR(N) asm volatile("s_waitcnt vmcnt(" #N ") lgkmcnt(0)\n\ts_barrier":::"memory")
;   #define RESC() do{ if(resc){ asm volatile("s_waitcnt lgkmcnt(0)":::"memory"); \
;       _Pragma("unroll") for(int d_=0;d_<2;++d_) _Pragma("unroll") for(int r=0;r<16;++r)o[d_][r]*=wsf[crow(r,hi)]; } }while(0)
;   #define ROT() do{sl_prev=sl_cur;sl_cur=sl_next;sl_next=(sl_next==(NSLOT-1)*SLOTB)?0:sl_next+SLOTB;}while(0)
; template<int THRL> __device__ __forceinline__ void attn_unit(long rowbase,int qb,int t0,bool WIN,bool NOMAX,const bf16*Qc,const bf16*__restrict__ Kc,const bf16*__restrict__ Vc,bf16*Oc,float s2,float sink2,char*shm,
;     bf16x8 (&qr)[4],bool pref,const bf16*qkvb,int vn,int in_){
;     ...
;   int t=1;
;     ...
;   for(;t+5<NT;t+=2){
;     STEP(pB0,pB1,pA0,pA1,t,true,true,true);     WAIT_BAR(2); RESC(); ROT();
;     STEP(pA0,pA1,pB0,pB1,t+1,true,true,true);   WAIT_BAR(2); RESC(); ROT();
.LBB0_342:
	s_or_b64 exec, exec, s[64:65]
	s_waitcnt lgkmcnt(14)
	v_mfma_f32_32x32x16_bf16 v[18:33], v[142:145], v[150:153], v[18:33]
	v_exp_f32_e32 v114, v114
	v_exp_f32_e32 v115, v115
	s_waitcnt lgkmcnt(12)
	v_mfma_f32_32x32x16_bf16 v[34:49], v[142:145], v[66:69], v[34:49]
	v_exp_f32_e32 v116, v116
	v_exp_f32_e32 v117, v117
	v_add_u32_e32 v62, s86, v231
	ds_read_b128 v[174:177], v62
	ds_read_b128 v[170:173], v62 offset:512
	s_waitcnt lgkmcnt(12)
	v_mfma_f32_32x32x16_bf16 v[18:33], v[138:141], v[70:73], v[18:33]
	v_exp_f32_e32 v118, v118
	v_exp_f32_e32 v119, v119
	ds_read_b128 v[166:169], v62 offset:2048
	ds_read_b128 v[162:165], v62 offset:2560
	s_waitcnt lgkmcnt(12)
	v_mfma_f32_32x32x16_bf16 v[34:49], v[138:141], v[74:77], v[34:49]
	v_exp_f32_e32 v120, v120
	v_exp_f32_e32 v121, v121
	ds_read_b128 v[158:161], v62 offset:4096
	ds_read_b128 v[154:157], v62 offset:4608
	s_waitcnt lgkmcnt(12)
	v_mfma_f32_32x32x16_bf16 v[18:33], v[134:137], v[78:81], v[18:33]
	v_exp_f32_e32 v122, v122
	v_exp_f32_e32 v123, v123
	ds_read_b128 v[150:153], v62 offset:6144
	ds_read_b128 v[146:149], v62 offset:6656
	s_waitcnt lgkmcnt(12)
	v_mfma_f32_32x32x16_bf16 v[34:49], v[134:137], v[50:53], v[34:49]
	v_exp_f32_e32 v124, v124
	v_exp_f32_e32 v125, v125
	s_waitcnt lgkmcnt(10)
	v_mfma_f32_32x32x16_bf16 v[18:33], v[130:133], v[54:57], v[18:33]
	v_exp_f32_e32 v126, v126
	v_exp_f32_e32 v127, v127
	s_waitcnt lgkmcnt(8)
	v_mfma_f32_32x32x16_bf16 v[34:49], v[130:133], v[58:61], v[34:49]
	v_exp_f32_e32 v128, v128
	v_exp_f32_e32 v129, v129
	ds_read_b64_tr_b16 v[50:51], v255 offset:24576
	ds_read_b64_tr_b16 v[52:53], v255 offset:25088
	ds_read_b64_tr_b16 v[54:55], v255 offset:28672
	ds_read_b64_tr_b16 v[56:57], v255 offset:29184
	ds_read_b64_tr_b16 v[58:59], v255 offset:25600
	ds_read_b64_tr_b16 v[60:61], v255 offset:26112
	ds_read_b64_tr_b16 v[62:63], v255 offset:29696
	ds_read_b64_tr_b16 v[64:65], v255 offset:30208
	ds_read_b64_tr_b16 v[66:67], v255 offset:26624
	ds_read_b64_tr_b16 v[68:69], v255 offset:27136
	ds_read_b64_tr_b16 v[70:71], v255 offset:30720
	ds_read_b64_tr_b16 v[72:73], v255 offset:31232
	ds_read_b64_tr_b16 v[74:75], v255 offset:27648
	ds_read_b64_tr_b16 v[76:77], v255 offset:28160
	ds_read_b64_tr_b16 v[78:79], v255 offset:31744
	ds_read_b64_tr_b16 v[80:81], v255 offset:32256
	v_exp_f32_e32 v98, v98
	v_exp_f32_e32 v99, v99
	v_exp_f32_e32 v100, v100
	v_exp_f32_e32 v101, v101
	v_exp_f32_e32 v102, v102
	v_exp_f32_e32 v103, v103
	v_exp_f32_e32 v104, v104
	v_exp_f32_e32 v105, v105
	s_waitcnt lgkmcnt(14)
	v_mfma_f32_32x32x16_bf16 v[236:251], v[142:145], v[50:53], v[236:251]
	v_cvt_f32_u32_e32 v50, s49
	v_mov_b32_e32 v185, v184
	v_fma_f32 v50, v184, v50, v186
	v_sub_f32_e32 v50, v50, v225
	v_exp_f32_e32 v106, v106
	s_waitcnt lgkmcnt(12)
	v_mfma_f32_32x32x16_bf16 v[200:215], v[142:145], v[54:57], v[200:215]
	v_fma_f32 v57, v185, s31, v50
	v_fma_f32 v56, v184, s30, v50
	v_fma_f32 v55, v185, s35, v50
	v_fma_f32 v54, v184, s34, v50
	v_exp_f32_e32 v107, v107
	s_waitcnt lgkmcnt(10)
	v_mfma_f32_32x32x16_bf16 v[236:251], v[138:141], v[58:61], v[236:251]
	v_fma_f32 v61, v185, s27, v50
	v_fma_f32 v60, v184, s26, v50
	v_fma_f32 v59, v185, s29, v50
	v_fma_f32 v58, v184, s28, v50
	v_exp_f32_e32 v108, v108
	s_waitcnt lgkmcnt(8)
	v_mfma_f32_32x32x16_bf16 v[200:215], v[138:141], v[62:65], v[200:215]
	v_fma_f32 v65, v185, s23, v50
	v_fma_f32 v64, v184, s22, v50
	v_fma_f32 v63, v185, s25, v50
	v_fma_f32 v62, v184, s24, v50
	v_exp_f32_e32 v109, v109
	s_waitcnt lgkmcnt(6)
	v_mfma_f32_32x32x16_bf16 v[236:251], v[134:137], v[66:69], v[236:251]
	v_fma_f32 v66, 0, v184, v50
	v_add_f32_e32 v67, v184, v50
	v_fma_f32 v69, v191, s9, v50
	v_fma_f32 v68, v190, s8, v50
	v_exp_f32_e32 v110, v110
	s_waitcnt lgkmcnt(4)
	v_mfma_f32_32x32x16_bf16 v[200:215], v[134:137], v[70:73], v[200:215]
	v_fma_f32 v71, v191, s11, v50
	v_fma_f32 v70, v190, s10, v50
	v_fma_f32 v73, v191, s13, v50
	v_fma_f32 v72, v190, s12, v50
	v_exp_f32_e32 v111, v111
	s_waitcnt lgkmcnt(2)
	v_mfma_f32_32x32x16_bf16 v[236:251], v[130:133], v[74:77], v[236:251]
	v_fma_f32 v75, v191, s15, v50
	v_fma_f32 v74, v190, s14, v50
	v_fma_f32 v77, v191, s17, v50
	v_fma_f32 v76, v190, s16, v50
	v_exp_f32_e32 v112, v112
	s_waitcnt lgkmcnt(0)
	v_mfma_f32_32x32x16_bf16 v[200:215], v[130:133], v[78:81], v[200:215]
	v_fma_f32 v79, v191, s19, v50
	v_fma_f32 v78, v190, s18, v50
	v_fma_f32 v81, v191, s21, v50
	v_fma_f32 v80, v190, s20, v50
	v_exp_f32_e32 v113, v113
	v_fma_f32 v53, v185, s37, v50
	v_fma_f32 v52, v184, s36, v50
	v_fma_f32 v51, v189, s93, v50
	v_fma_f32 v50, v188, s92, v50
	s_add_i32 s100, s66, s50
	s_mov_b32 s101, m0
	s_mov_b32 m0, s100
	s_nop 0
	global_load_lds_dwordx4 v[198:199], off
	s_add_i32 s100, s86, s79
	s_mov_b32 m0, s100
	s_nop 0
	global_load_lds_dwordx4 v[196:197], off
	s_add_i32 m0, s100, 0xe780
	s_nop 0
	global_load_lds_dwordx4 v[196:197], off offset:128
	s_mov_b32 m0, s101
	s_add_i32 s67, s67, 2
	s_add_i32 s100, s86, 0x2000
	s_cmpk_lg_i32 s86, 0x4000
	s_cselect_b32 s87, s100, 0
	s_addk_i32 s49, 0x80
	v_lshl_add_u64 v[196:197], v[196:197], 0, s[0:1]
	v_lshl_add_u64 v[198:199], v[198:199], 0, s[0:1]
	s_cmp_ge_i32 s67, s48
	s_cselect_b32 s101, 1, 0
	s_nop 0
	s_waitcnt vmcnt(3) lgkmcnt(0)
	s_barrier
	s_and_saveexec_b64 s[64:65], s[44:45]
	s_cbranch_execz .LBB0_344
	s_waitcnt lgkmcnt(0)
	ds_read_b128 v[84:87], v227 offset:49248
	ds_read_b128 v[88:91], v227 offset:49216
	ds_read_b128 v[92:95], v227 offset:49184
	s_waitcnt lgkmcnt(2)
	v_pk_mul_f32 v[32:33], v[32:33], v[86:87]
	v_pk_mul_f32 v[30:31], v[30:31], v[84:85]
	v_pk_mul_f32 v[48:49], v[48:49], v[86:87]
	v_pk_mul_f32 v[46:47], v[46:47], v[84:85]
	v_pk_mul_f32 v[250:251], v[250:251], v[86:87]
	v_pk_mul_f32 v[248:249], v[248:249], v[84:85]
	v_pk_mul_f32 v[214:215], v[214:215], v[86:87]
	v_pk_mul_f32 v[212:213], v[212:213], v[84:85]
	ds_read_b128 v[84:87], v227 offset:49152
	s_waitcnt lgkmcnt(2)
	v_pk_mul_f32 v[28:29], v[28:29], v[90:91]
	v_pk_mul_f32 v[26:27], v[26:27], v[88:89]
	v_pk_mul_f32 v[44:45], v[44:45], v[90:91]
	v_pk_mul_f32 v[42:43], v[42:43], v[88:89]
	v_pk_mul_f32 v[246:247], v[246:247], v[90:91]
	v_pk_mul_f32 v[244:245], v[244:245], v[88:89]
	v_pk_mul_f32 v[210:211], v[210:211], v[90:91]
	v_pk_mul_f32 v[208:209], v[208:209], v[88:89]
	s_waitcnt lgkmcnt(1)
	v_pk_mul_f32 v[24:25], v[24:25], v[94:95]
	v_pk_mul_f32 v[22:23], v[22:23], v[92:93]
	v_pk_mul_f32 v[40:41], v[40:41], v[94:95]
	v_pk_mul_f32 v[38:39], v[38:39], v[92:93]
	v_pk_mul_f32 v[242:243], v[242:243], v[94:95]
	v_pk_mul_f32 v[240:241], v[240:241], v[92:93]
	v_pk_mul_f32 v[206:207], v[206:207], v[94:95]
	v_pk_mul_f32 v[204:205], v[204:205], v[92:93]
	s_waitcnt lgkmcnt(0)
	v_pk_mul_f32 v[20:21], v[20:21], v[86:87]
	v_pk_mul_f32 v[18:19], v[18:19], v[84:85]
	v_pk_mul_f32 v[36:37], v[36:37], v[86:87]
	v_pk_mul_f32 v[34:35], v[34:35], v[84:85]
	v_pk_mul_f32 v[238:239], v[238:239], v[86:87]
	v_pk_mul_f32 v[236:237], v[236:237], v[84:85]
	v_pk_mul_f32 v[202:203], v[202:203], v[86:87]
	v_pk_mul_f32 v[200:201], v[200:201], v[84:85]
; #define WAIT_BAR(N) asm volatile("s_waitcnt vmcnt(" #N ") lgkmcnt(0)\n\ts_barrier":::"memory")
;   #define RESC() do{ if(resc){ asm volatile("s_waitcnt lgkmcnt(0)":::"memory"); \
;       _Pragma("unroll") for(int d_=0;d_<2;++d_) _Pragma("unroll") for(int r=0;r<16;++r)o[d_][r]*=wsf[crow(r,hi)]; } }while(0)
;   #define ROT() do{sl_prev=sl_cur;sl_cur=sl_next;sl_next=(sl_next==(NSLOT-1)*SLOTB)?0:sl_next+SLOTB;}while(0)
; template<int THRL> __device__ __forceinline__ void attn_unit(long rowbase,int qb,int t0,bool WIN,bool NOMAX,const bf16*Qc,const bf16*__restrict__ Kc,const bf16*__restrict__ Vc,bf16*Oc,float s2,float sink2,char*shm,
;     bf16x8 (&qr)[4],bool pref,const bf16*qkvb,int vn,int in_){
;     ...
;   for(;t+5<NT;t+=2){
;     STEP(pB0,pB1,pA0,pA1,t,true,true,true);     WAIT_BAR(2); RESC(); ROT();
;     STEP(pA0,pA1,pB0,pB1,t+1,true,true,true);   WAIT_BAR(2); RESC(); ROT();
;   }
.LBB0_344:
	s_or_b64 exec, exec, s[64:65]
	s_cmp_lg_u32 s101, 0
	s_cbranch_scc1 .LBB0_356
	s_mov_b32 s44, s66
	s_mov_b32 s51, s86
	s_mov_b32 s66, s87
	s_branch .LBB0_334
